# GEMM K-loops: A-fragment LDS stage bases folded into ds_read offsets (lane-offset register biased once per phase; 4 VALU adds per iteration removed)
# baseline (speedup 1.0000x reference)
.LBB0_282:
	s_or_b64 exec, exec, s[12:13]
	v_lshrrev_b32_e32 v9, 1, v233
	v_and_b32_e32 v9, 24, v9
	v_and_b32_e32 v5, 15, v233
	v_lshlrev_b32_e32 v146, 1, v9
	s_add_u32 s49, s0, 0x4a00000
	v_lshl_or_b32 v1, s16, 6, v5
	v_lshl_or_b32 v10, v5, 6, v146
	v_lshlrev_b32_e32 v5, 2, v5
	s_addc_u32 s50, s1, 0
	s_and_b32 s51, s9, 3
	s_lshl_b32 s4, s16, 13
	v_and_b32_e32 v11, 32, v5
	v_bitop3_b32 v12, v10, s4, v11 bitop3:0xde
	s_lshl_b32 s4, s51, 12
	v_bitop3_b32 v147, s4, v10, v11 bitop3:0xf6
	v_add_u32_e32 v147, 0x10000, v147
	v_cvt_f32_ubyte0_e32 v10, v9
	v_mov_b32_e32 v11, 0xc029b21d
	v_fmamk_f32 v10, v10, 0xbed49a78, v11
	v_exp_f32_e32 v148, v10
	v_or_b32_e32 v10, 1, v9
	v_cvt_f32_ubyte0_e32 v10, v10
	v_fmamk_f32 v10, v10, 0xbed49a78, v11
	v_exp_f32_e32 v149, v10
	v_or_b32_e32 v10, 2, v9
	v_cvt_f32_ubyte0_e32 v10, v10
	v_fmamk_f32 v10, v10, 0xbed49a78, v11
	v_exp_f32_e32 v150, v10
	v_or_b32_e32 v10, 3, v9
	s_cmpk_lt_u32 s14, 0x100
	v_cvt_f32_ubyte0_e32 v10, v10
	v_readlane_b32 s14, v254, 47
	s_cselect_b64 s[12:13], -1, 0
	v_fmamk_f32 v10, v10, 0xbed49a78, v11
	s_ashr_i32 s52, s98, 31
	s_ashr_i32 s53, s14, 31
	v_exp_f32_e32 v151, v10
	v_or_b32_e32 v10, 4, v9
	v_readlane_b32 s15, v254, 48
	s_add_u32 s14, s0, 0x1200
	v_cvt_f32_ubyte0_e32 v10, v10
	s_addc_u32 s15, s1, 0
	s_lshl_b32 s16, s16, 8
	v_fmamk_f32 v10, v10, 0xbed49a78, v11
	s_add_i32 s16, s16, 0
	v_exp_f32_e32 v152, v10
	v_or_b32_e32 v10, 5, v9
	s_add_i32 s16, s16, 0x21000
	v_cvt_f32_ubyte0_e32 v10, v10
	v_add_u32_e32 v156, s16, v5
	v_lshlrev_b32_e32 v5, 14, v6
	v_fmamk_f32 v10, v10, 0xbed49a78, v11
	v_and_b32_e32 v5, 0xffff8000, v5
	v_exp_f32_e32 v153, v10
	v_or_b32_e32 v10, 6, v9
	v_or_b32_e32 v9, 7, v9
	v_lshl_add_u32 v5, v7, 11, v5
	v_and_b32_e32 v6, 1, v6
	v_cvt_f32_ubyte0_e32 v10, v10
	v_cvt_f32_ubyte0_e32 v9, v9
	v_lshl_or_b32 v5, v6, 6, v5
	v_fmamk_f32 v10, v10, 0xbed49a78, v11
	v_fmamk_f32 v9, v9, 0xbed49a78, v11
	v_lshl_add_u32 v138, v8, 1, v5
	v_lshlrev_b32_e32 v5, 14, v2
	v_exp_f32_e32 v154, v10
	v_exp_f32_e32 v155, v9
	v_and_b32_e32 v5, 0xffff8000, v5
	v_lshl_add_u32 v3, v3, 11, v5
	v_and_b32_e32 v2, 1, v2
	v_lshl_or_b32 v2, v2, 6, v3
	s_mov_b32 s9, 0
	v_cmp_eq_u32_e64 s[4:5], 0, v234
	v_mov_b32_e32 v139, v0
	v_lshl_add_u32 v140, v4, 1, v2
	v_mov_b32_e32 v141, v0
	v_add_u32_e32 v157, 0, v12
	s_xor_b64 s[16:17], s[6:7], -1
	s_branch .LBB0_285

.LBB0_287:
	s_ashr_i32 s21, s20, 31
	s_lshl_b64 s[22:23], s[20:21], 19
	s_add_u32 s22, s80, s22
	s_addc_u32 s23, s81, s23
	s_and_b64 s[24:25], s[6:7], exec
	s_cselect_b32 s21, s23, s29
	s_cselect_b32 s36, s22, s28
	s_ashr_i32 s19, s18, 31
	s_lshl_b64 s[24:25], s[18:19], 19
	s_add_u32 s24, s40, s24
	s_addc_u32 s25, s41, s25
	s_and_b64 s[34:35], s[6:7], exec
	s_cselect_b32 s19, s25, s31
	s_cselect_b32 s37, s24, s30
	s_add_u32 s38, s30, 0x100
	s_addc_u32 s39, s31, 0
	s_add_u32 s28, s28, 0x40080
	s_addc_u32 s29, s29, 0
	s_mov_b32 s55, -2
	s_add_u32 s30, s28, 0xfffc0080
	s_addc_u32 s31, s29, -1
	s_add_i32 s56, 0, 0x10000
	s_cmp_eq_u32 s55, 12
	s_cselect_b32 s35, s21, s31
	s_cselect_b32 s34, s36, s30
	s_cselect_b32 s31, s19, s39
	s_cselect_b32 s30, s37, s38
	s_add_i32 s58, 0, 0x14000
	ds_read_b128 v[142:145], v147
	ds_read_b128 v[158:161], v147 offset:1024
	ds_read_b128 v[162:165], v147 offset:2048
	ds_read_b128 v[166:169], v147 offset:3072
	ds_read_b128 v[170:173], v147 offset:16384
	ds_read_b128 v[174:177], v147 offset:17408
	ds_read_b128 v[178:181], v147 offset:18432
	ds_read_b128 v[182:185], v147 offset:19456
	v_lshl_add_u64 v[224:225], s[28:29], 0, v[140:141]
	s_add_i32 m0, s44, 0xc000
	ds_read_b128 v[186:189], v157
	ds_read_b128 v[190:193], v157 offset:1024
	ds_read_b128 v[194:197], v157 offset:2048
	ds_read_b128 v[198:201], v157 offset:3072
	ds_read_b128 v[202:205], v157 offset:4096
	ds_read_b128 v[206:209], v157 offset:5120
	ds_read_b128 v[220:223], v157 offset:6144
	ds_read_b128 v[236:239], v157 offset:7168
	global_load_lds_dwordx4 v[224:225], off
	s_add_i32 m0, s44, 0xe000
	v_lshl_add_u64 v[224:225], s[28:29], 0, v[138:139]
	global_load_lds_dwordx4 v[224:225], off
	s_branch .Lpadj_0
	s_nop 0
	s_nop 0
	s_nop 0
	s_nop 0
	s_nop 0

.Lpadj_1:
	s_waitcnt vmcnt(8)
	s_waitcnt lgkmcnt(0)
	s_barrier
	v_mfma_f32_16x16x32_bf16 v[62:65], v[142:145], v[186:189], 0
	v_mfma_f32_16x16x32_bf16 v[58:61], v[162:165], v[186:189], 0
	v_mfma_f32_16x16x32_bf16 v[46:49], v[142:145], v[194:197], 0
	v_mfma_f32_16x16x32_bf16 v[42:45], v[162:165], v[194:197], 0
	v_mfma_f32_16x16x32_bf16 v[30:33], v[142:145], v[202:205], 0
	v_mfma_f32_16x16x32_bf16 v[26:29], v[162:165], v[202:205], 0
	v_mfma_f32_16x16x32_bf16 v[14:17], v[142:145], v[220:223], 0
	v_mfma_f32_16x16x32_bf16 v[10:13], v[162:165], v[220:223], 0
	v_mfma_f32_16x16x32_bf16 v[62:65], v[158:161], v[190:193], v[62:65]
	v_mfma_f32_16x16x32_bf16 v[58:61], v[166:169], v[190:193], v[58:61]
	v_mfma_f32_16x16x32_bf16 v[46:49], v[158:161], v[198:201], v[46:49]
	v_mfma_f32_16x16x32_bf16 v[42:45], v[166:169], v[198:201], v[42:45]
	v_mfma_f32_16x16x32_bf16 v[30:33], v[158:161], v[206:209], v[30:33]
	v_mfma_f32_16x16x32_bf16 v[26:29], v[166:169], v[206:209], v[26:29]
	v_mfma_f32_16x16x32_bf16 v[14:17], v[158:161], v[236:239], v[14:17]
	v_mfma_f32_16x16x32_bf16 v[10:13], v[166:169], v[236:239], v[10:13]
	v_mfma_f32_16x16x32_bf16 v[54:57], v[170:173], v[186:189], 0
	v_mfma_f32_16x16x32_bf16 v[50:53], v[178:181], v[186:189], 0
	v_mfma_f32_16x16x32_bf16 v[38:41], v[170:173], v[194:197], 0
	v_mfma_f32_16x16x32_bf16 v[34:37], v[178:181], v[194:197], 0
	v_mfma_f32_16x16x32_bf16 v[22:25], v[170:173], v[202:205], 0
	v_mfma_f32_16x16x32_bf16 v[18:21], v[178:181], v[202:205], 0
	v_mfma_f32_16x16x32_bf16 v[6:9], v[170:173], v[220:223], 0
	v_mfma_f32_16x16x32_bf16 v[2:5], v[178:181], v[220:223], 0
	v_mfma_f32_16x16x32_bf16 v[54:57], v[174:177], v[190:193], v[54:57]
	v_mfma_f32_16x16x32_bf16 v[50:53], v[182:185], v[190:193], v[50:53]
	v_mfma_f32_16x16x32_bf16 v[38:41], v[174:177], v[198:201], v[38:41]
	v_mfma_f32_16x16x32_bf16 v[34:37], v[182:185], v[198:201], v[34:37]
	v_mfma_f32_16x16x32_bf16 v[22:25], v[174:177], v[206:209], v[22:25]
	v_mfma_f32_16x16x32_bf16 v[18:21], v[182:185], v[206:209], v[18:21]
	v_mfma_f32_16x16x32_bf16 v[6:9], v[174:177], v[236:239], v[6:9]
	v_mfma_f32_16x16x32_bf16 v[2:5], v[182:185], v[236:239], v[2:5]
	s_barrier
	s_add_i32 s56, 0, 0x18000
	s_add_i32 s57, 0, 0x1c000
	ds_read_b128 v[142:145], v147 offset:32768
	ds_read_b128 v[158:161], v147 offset:33792
	ds_read_b128 v[162:165], v147 offset:34816
	ds_read_b128 v[166:169], v147 offset:35840
	ds_read_b128 v[170:173], v147 offset:49152
	ds_read_b128 v[174:177], v147 offset:50176
	ds_read_b128 v[178:181], v147 offset:51200
	ds_read_b128 v[182:185], v147 offset:52224
	s_add_u32 s34, s34, 0x40000
	s_addc_u32 s35, s35, 0
	s_mov_b32 m0, s43
	v_lshl_add_u64 v[244:245], s[34:35], 0, v[130:131]
	ds_read_b128 v[186:189], v157 offset:32768
	ds_read_b128 v[190:193], v157 offset:33792
	ds_read_b128 v[194:197], v157 offset:34816
	ds_read_b128 v[198:201], v157 offset:35840
	ds_read_b128 v[202:205], v157 offset:36864
	ds_read_b128 v[206:209], v157 offset:37888
	ds_read_b128 v[220:223], v157 offset:38912
	ds_read_b128 v[236:239], v157 offset:39936
	global_load_lds_dwordx4 v[244:245], off
	s_mov_b32 m0, s46
	v_lshl_add_u64 v[244:245], s[34:35], 0, v[134:135]
	global_load_lds_dwordx4 v[244:245], off
	s_branch .Lpadj_2
	s_nop 0
	s_nop 0
	s_nop 0
	s_nop 0
	s_nop 0
	s_nop 0
	s_nop 0
	s_nop 0
	s_nop 0
	s_nop 0

.LBB0_288:
	s_add_u32 s30, s28, 0xfffc0080
	s_addc_u32 s31, s29, -1
	s_add_i32 s56, 0, 0x10000
	s_cmp_eq_u32 s55, 12
	s_cselect_b32 s35, s21, s31
	s_cselect_b32 s34, s36, s30
	s_cselect_b32 s31, s19, s39
	s_cselect_b32 s30, s37, s38
	s_add_i32 s58, 0, 0x14000
	ds_read_b128 v[142:145], v147
	ds_read_b128 v[158:161], v147 offset:1024
	ds_read_b128 v[162:165], v147 offset:2048
	ds_read_b128 v[166:169], v147 offset:3072
	ds_read_b128 v[170:173], v147 offset:16384
	ds_read_b128 v[174:177], v147 offset:17408
	ds_read_b128 v[178:181], v147 offset:18432
	ds_read_b128 v[182:185], v147 offset:19456
	s_add_i32 m0, s44, 0xc000
	ds_read_b128 v[186:189], v157
	ds_read_b128 v[190:193], v157 offset:1024
	ds_read_b128 v[194:197], v157 offset:2048
	ds_read_b128 v[198:201], v157 offset:3072
	ds_read_b128 v[202:205], v157 offset:4096
	ds_read_b128 v[206:209], v157 offset:5120
	ds_read_b128 v[220:223], v157 offset:6144
	ds_read_b128 v[236:239], v157 offset:7168
	global_load_lds_dwordx4 v140, s[28:29]
	s_add_i32 m0, s44, 0xe000
	s_nop 0
	global_load_lds_dwordx4 v138, s[28:29]
	s_branch .Lpadj_4
	s_nop 0
	s_nop 0
	s_nop 0
	s_nop 0
	s_nop 0
	s_nop 0
	s_nop 0
	s_nop 0
	s_nop 0
	s_nop 0
	s_nop 0
	s_nop 0
	s_nop 0
	s_nop 0

.Lpadj_5:
	s_waitcnt vmcnt(8)
	s_waitcnt lgkmcnt(0)
	s_barrier
	v_mfma_f32_16x16x32_bf16 v[62:65], v[142:145], v[186:189], v[62:65]
	v_mfma_f32_16x16x32_bf16 v[58:61], v[162:165], v[186:189], v[58:61]
	v_mfma_f32_16x16x32_bf16 v[46:49], v[142:145], v[194:197], v[46:49]
	v_mfma_f32_16x16x32_bf16 v[42:45], v[162:165], v[194:197], v[42:45]
	v_mfma_f32_16x16x32_bf16 v[30:33], v[142:145], v[202:205], v[30:33]
	v_mfma_f32_16x16x32_bf16 v[26:29], v[162:165], v[202:205], v[26:29]
	v_mfma_f32_16x16x32_bf16 v[14:17], v[142:145], v[220:223], v[14:17]
	v_mfma_f32_16x16x32_bf16 v[10:13], v[162:165], v[220:223], v[10:13]
	v_mfma_f32_16x16x32_bf16 v[62:65], v[158:161], v[190:193], v[62:65]
	v_mfma_f32_16x16x32_bf16 v[58:61], v[166:169], v[190:193], v[58:61]
	v_mfma_f32_16x16x32_bf16 v[46:49], v[158:161], v[198:201], v[46:49]
	v_mfma_f32_16x16x32_bf16 v[42:45], v[166:169], v[198:201], v[42:45]
	v_mfma_f32_16x16x32_bf16 v[30:33], v[158:161], v[206:209], v[30:33]
	v_mfma_f32_16x16x32_bf16 v[26:29], v[166:169], v[206:209], v[26:29]
	v_mfma_f32_16x16x32_bf16 v[14:17], v[158:161], v[236:239], v[14:17]
	v_mfma_f32_16x16x32_bf16 v[10:13], v[166:169], v[236:239], v[10:13]
	v_mfma_f32_16x16x32_bf16 v[54:57], v[170:173], v[186:189], v[54:57]
	v_mfma_f32_16x16x32_bf16 v[50:53], v[178:181], v[186:189], v[50:53]
	v_mfma_f32_16x16x32_bf16 v[38:41], v[170:173], v[194:197], v[38:41]
	v_mfma_f32_16x16x32_bf16 v[34:37], v[178:181], v[194:197], v[34:37]
	v_mfma_f32_16x16x32_bf16 v[22:25], v[170:173], v[202:205], v[22:25]
	v_mfma_f32_16x16x32_bf16 v[18:21], v[178:181], v[202:205], v[18:21]
	v_mfma_f32_16x16x32_bf16 v[6:9], v[170:173], v[220:223], v[6:9]
	v_mfma_f32_16x16x32_bf16 v[2:5], v[178:181], v[220:223], v[2:5]
	v_mfma_f32_16x16x32_bf16 v[54:57], v[174:177], v[190:193], v[54:57]
	v_mfma_f32_16x16x32_bf16 v[50:53], v[182:185], v[190:193], v[50:53]
	v_mfma_f32_16x16x32_bf16 v[38:41], v[174:177], v[198:201], v[38:41]
	v_mfma_f32_16x16x32_bf16 v[34:37], v[182:185], v[198:201], v[34:37]
	v_mfma_f32_16x16x32_bf16 v[22:25], v[174:177], v[206:209], v[22:25]
	v_mfma_f32_16x16x32_bf16 v[18:21], v[182:185], v[206:209], v[18:21]
	v_mfma_f32_16x16x32_bf16 v[6:9], v[174:177], v[236:239], v[6:9]
	v_mfma_f32_16x16x32_bf16 v[2:5], v[182:185], v[236:239], v[2:5]
	s_barrier
	s_add_i32 s56, 0, 0x18000
	s_add_i32 s57, 0, 0x1c000
	ds_read_b128 v[142:145], v147 offset:32768
	ds_read_b128 v[158:161], v147 offset:33792
	ds_read_b128 v[162:165], v147 offset:34816
	ds_read_b128 v[166:169], v147 offset:35840
	ds_read_b128 v[170:173], v147 offset:49152
	ds_read_b128 v[174:177], v147 offset:50176
	ds_read_b128 v[178:181], v147 offset:51200
	ds_read_b128 v[182:185], v147 offset:52224
	s_add_u32 s34, s34, 0x40000
	s_addc_u32 s35, s35, 0
	s_mov_b32 m0, s43
	ds_read_b128 v[186:189], v157 offset:32768
	ds_read_b128 v[190:193], v157 offset:33792
	ds_read_b128 v[194:197], v157 offset:34816
	ds_read_b128 v[198:201], v157 offset:35840
	ds_read_b128 v[202:205], v157 offset:36864
	ds_read_b128 v[206:209], v157 offset:37888
	ds_read_b128 v[220:223], v157 offset:38912
	ds_read_b128 v[236:239], v157 offset:39936
	global_load_lds_dwordx4 v130, s[34:35]
	s_mov_b32 m0, s46
	s_nop 0
	global_load_lds_dwordx4 v134, s[34:35]
	s_branch .Lpadj_6
	s_nop 0
	s_nop 0
	s_nop 0
	s_nop 0
	s_nop 0
	s_nop 0
	s_nop 0
	s_nop 0
	s_nop 0
	s_nop 0
	s_nop 0
	s_nop 0
	s_nop 0

.LBB0_357:
	s_lshl_b32 s6, s17, 5
	s_and_b32 s20, s6, 0x60
	s_add_i32 m0, s48, 0x18000
	v_lshl_add_u64 v[2:3], v[2:3], 0, s[96:97]
	s_lshl_b32 s5, s18, 13
	s_lshl_b32 s17, s20, 7
	s_waitcnt vmcnt(2)
	s_barrier
	global_load_lds_dwordx4 v[2:3], off
	v_lshl_add_u64 v[2:3], v[4:5], 0, s[96:97]
	s_add_i32 m0, s48, 0x1a000
	s_add_i32 s52, s48, 0x8000
	s_add_i32 s53, s48, 0xa000
	global_load_lds_dwordx4 v[2:3], off
	v_lshl_add_u64 v[2:3], v[6:7], 0, s[96:97]
	s_mov_b32 m0, s52
	s_add_u32 s6, s30, 0x40080
	global_load_lds_dwordx4 v[2:3], off
	v_lshl_add_u64 v[2:3], v[8:9], 0, s[96:97]
	s_mov_b32 m0, s53
	s_addc_u32 s7, s31, 0
	global_load_lds_dwordx4 v[2:3], off
	s_add_i32 m0, s48, 0x1c000
	v_lshl_add_u64 v[2:3], s[6:7], 0, v[134:135]
	global_load_lds_dwordx4 v[2:3], off
	v_lshl_add_u64 v[2:3], s[6:7], 0, v[130:131]
	s_add_i32 m0, s48, 0x1e000
	s_sext_i32_i16 s29, s4
	global_load_lds_dwordx4 v[2:3], off
	v_lshrrev_b32_e32 v2, 1, v233
	v_and_b32_e32 v2, 24, v2
	v_lshlrev_b32_e32 v3, 6, v1
	v_lshlrev_b32_e32 v4, 1, v2
	s_movk_i32 s4, 0x3c0
	v_lshlrev_b32_e32 v5, 2, v1
	v_and_or_b32 v3, v3, s4, v4
	v_and_b32_e32 v5, 32, v5
	v_bitop3_b32 v3, v3, s5, v5 bitop3:0xde
	v_lshlrev_b32_e32 v5, 2, v11
	v_or_b32_e32 v156, s20, v2
	v_lshlrev_b32_e32 v2, 14, v10
	v_lshl_or_b32 v4, v11, 6, v4
	v_and_b32_e32 v5, 32, v5
	v_and_b32_e32 v2, 0xffff8000, v2
	v_bitop3_b32 v155, s17, v4, v5 bitop3:0xf6
	v_add_u32_e32 v155, 0x10000, v155
	v_lshl_add_u32 v2, v12, 11, v2
	v_and_b32_e32 v4, 1, v10
	v_lshl_or_b32 v2, v4, 6, v2
	v_lshl_add_u32 v138, v13, 1, v2
	v_lshlrev_b32_e32 v2, 14, v15
	s_cmpk_lt_u32 s16, 0x100
	v_and_b32_e32 v2, 0xffff8000, v2
	s_waitcnt vmcnt(6)
	s_cselect_b64 s[16:17], -1, 0
	s_ashr_i32 s54, s98, 31
	v_lshl_add_u32 v2, v14, 11, v2
	v_and_b32_e32 v4, 1, v15
	s_add_u32 s18, s0, 0x1200
	v_lshl_or_b32 v2, v4, 6, v2
	s_mov_b32 s38, 0
	v_cmp_eq_u32_e64 s[4:5], 0, v234
	s_addc_u32 s19, s1, 0
	v_mov_b32_e32 v139, v0
	v_lshl_add_u32 v140, v16, 1, v2
	v_mov_b32_e32 v141, v0
	v_add_u32_e32 v157, 0, v3
	s_barrier
	s_branch .LBB0_360

.LBB0_362:
	s_ashr_i32 s23, s22, 31
	s_lshl_b64 s[24:25], s[22:23], 19
	s_add_u32 s24, s80, s24
	s_addc_u32 s25, s81, s25
	s_and_b64 s[26:27], s[6:7], exec
	s_cselect_b32 s23, s25, s35
	s_cselect_b32 s39, s24, s34
	s_ashr_i32 s21, s20, 31
	s_lshl_b64 s[26:27], s[20:21], 19
	s_add_u32 s26, s45, s26
	s_addc_u32 s27, s46, s27
	s_and_b64 s[36:37], s[6:7], exec
	s_cselect_b32 s21, s27, s31
	s_cselect_b32 s40, s26, s30
	s_add_u32 s41, s30, 0x100
	s_addc_u32 s43, s31, 0
	s_add_u32 s30, s34, 0x40080
	s_addc_u32 s31, s35, 0
	s_mov_b32 s56, -2
	s_add_u32 s34, s30, 0xfffc0080
	s_addc_u32 s35, s31, -1
	s_add_i32 s57, 0, 0x10000
	s_cmp_eq_u32 s56, 12
	s_cselect_b32 s37, s23, s35
	s_cselect_b32 s36, s39, s34
	s_cselect_b32 s35, s21, s43
	s_cselect_b32 s34, s40, s41
	s_add_i32 s60, 0, 0x14000
	ds_read_b128 v[142:145], v155
	ds_read_b128 v[168:171], v155 offset:1024
	ds_read_b128 v[172:175], v155 offset:2048
	ds_read_b128 v[176:179], v155 offset:3072
	ds_read_b128 v[180:183], v155 offset:16384
	ds_read_b128 v[184:187], v155 offset:17408
	ds_read_b128 v[188:191], v155 offset:18432
	ds_read_b128 v[192:195], v155 offset:19456
	v_lshl_add_u64 v[146:147], s[30:31], 0, v[140:141]
	s_add_i32 m0, s48, 0xc000
	ds_read_b128 v[196:199], v157
	ds_read_b128 v[200:203], v157 offset:1024
	ds_read_b128 v[204:207], v157 offset:2048
	ds_read_b128 v[220:223], v157 offset:3072
	ds_read_b128 v[236:239], v157 offset:4096
	ds_read_b128 v[240:243], v157 offset:5120
	ds_read_b128 v[244:247], v157 offset:6144
	ds_read_b128 v[248:251], v157 offset:7168
	global_load_lds_dwordx4 v[146:147], off
	s_add_i32 m0, s48, 0xe000
	v_lshl_add_u64 v[146:147], s[30:31], 0, v[138:139]
	global_load_lds_dwordx4 v[146:147], off
	s_branch .Lpadj_8
	s_nop 0
	s_nop 0
	s_nop 0
	s_nop 0
	s_nop 0
	s_nop 0
	s_nop 0

.Lpadj_9:
	s_waitcnt vmcnt(8)
	s_waitcnt lgkmcnt(0)
	s_barrier
	v_mfma_f32_16x16x32_bf16 v[62:65], v[142:145], v[196:199], 0
	v_mfma_f32_16x16x32_bf16 v[54:57], v[172:175], v[196:199], 0
	v_mfma_f32_16x16x32_bf16 v[46:49], v[142:145], v[204:207], 0
	v_mfma_f32_16x16x32_bf16 v[38:41], v[172:175], v[204:207], 0
	v_mfma_f32_16x16x32_bf16 v[30:33], v[142:145], v[236:239], 0
	v_mfma_f32_16x16x32_bf16 v[22:25], v[172:175], v[236:239], 0
	v_mfma_f32_16x16x32_bf16 v[14:17], v[142:145], v[244:247], 0
	v_mfma_f32_16x16x32_bf16 v[6:9], v[172:175], v[244:247], 0
	v_mfma_f32_16x16x32_bf16 v[62:65], v[168:171], v[200:203], v[62:65]
	v_mfma_f32_16x16x32_bf16 v[54:57], v[176:179], v[200:203], v[54:57]
	v_mfma_f32_16x16x32_bf16 v[46:49], v[168:171], v[220:223], v[46:49]
	v_mfma_f32_16x16x32_bf16 v[38:41], v[176:179], v[220:223], v[38:41]
	v_mfma_f32_16x16x32_bf16 v[30:33], v[168:171], v[240:243], v[30:33]
	v_mfma_f32_16x16x32_bf16 v[22:25], v[176:179], v[240:243], v[22:25]
	v_mfma_f32_16x16x32_bf16 v[14:17], v[168:171], v[248:251], v[14:17]
	v_mfma_f32_16x16x32_bf16 v[6:9], v[176:179], v[248:251], v[6:9]
	v_mfma_f32_16x16x32_bf16 v[58:61], v[180:183], v[196:199], 0
	v_mfma_f32_16x16x32_bf16 v[50:53], v[188:191], v[196:199], 0
	v_mfma_f32_16x16x32_bf16 v[42:45], v[180:183], v[204:207], 0
	v_mfma_f32_16x16x32_bf16 v[34:37], v[188:191], v[204:207], 0
	v_mfma_f32_16x16x32_bf16 v[26:29], v[180:183], v[236:239], 0
	v_mfma_f32_16x16x32_bf16 v[18:21], v[188:191], v[236:239], 0
	v_mfma_f32_16x16x32_bf16 v[10:13], v[180:183], v[244:247], 0
	v_mfma_f32_16x16x32_bf16 v[2:5], v[188:191], v[244:247], 0
	v_mfma_f32_16x16x32_bf16 v[58:61], v[184:187], v[200:203], v[58:61]
	v_mfma_f32_16x16x32_bf16 v[50:53], v[192:195], v[200:203], v[50:53]
	v_mfma_f32_16x16x32_bf16 v[42:45], v[184:187], v[220:223], v[42:45]
	v_mfma_f32_16x16x32_bf16 v[34:37], v[192:195], v[220:223], v[34:37]
	v_mfma_f32_16x16x32_bf16 v[26:29], v[184:187], v[240:243], v[26:29]
	v_mfma_f32_16x16x32_bf16 v[18:21], v[192:195], v[240:243], v[18:21]
	v_mfma_f32_16x16x32_bf16 v[10:13], v[184:187], v[248:251], v[10:13]
	v_mfma_f32_16x16x32_bf16 v[2:5], v[192:195], v[248:251], v[2:5]
	s_barrier
	s_add_i32 s57, 0, 0x18000
	s_add_i32 s58, 0, 0x1c000
	ds_read_b128 v[142:145], v155 offset:32768
	ds_read_b128 v[168:171], v155 offset:33792
	ds_read_b128 v[172:175], v155 offset:34816
	ds_read_b128 v[176:179], v155 offset:35840
	ds_read_b128 v[180:183], v155 offset:49152
	ds_read_b128 v[184:187], v155 offset:50176
	ds_read_b128 v[188:191], v155 offset:51200
	ds_read_b128 v[192:195], v155 offset:52224
	s_add_u32 s36, s36, 0x40000
	s_addc_u32 s37, s37, 0
	s_mov_b32 m0, s50
	v_lshl_add_u64 v[252:253], s[36:37], 0, v[136:137]
	ds_read_b128 v[196:199], v157 offset:32768
	ds_read_b128 v[200:203], v157 offset:33792
	ds_read_b128 v[204:207], v157 offset:34816
	ds_read_b128 v[220:223], v157 offset:35840
	ds_read_b128 v[236:239], v157 offset:36864
	ds_read_b128 v[240:243], v157 offset:37888
	ds_read_b128 v[244:247], v157 offset:38912
	ds_read_b128 v[248:251], v157 offset:39936
	global_load_lds_dwordx4 v[252:253], off
	s_mov_b32 m0, s51
	v_lshl_add_u64 v[252:253], s[36:37], 0, v[132:133]
	global_load_lds_dwordx4 v[252:253], off
	s_branch .Lpadj_10
	s_nop 0
	s_nop 0
	s_nop 0
	s_nop 0
	s_nop 0
	s_nop 0
	s_nop 0
	s_nop 0
	s_nop 0
	s_nop 0

.LBB0_363:
	s_add_u32 s34, s30, 0xfffc0080
	s_addc_u32 s35, s31, -1
	s_add_i32 s57, 0, 0x10000
	s_cmp_eq_u32 s56, 12
	s_cselect_b32 s37, s23, s35
	s_cselect_b32 s36, s39, s34
	s_cselect_b32 s35, s21, s43
	s_cselect_b32 s34, s40, s41
	s_add_i32 s60, 0, 0x14000
	ds_read_b128 v[142:145], v155
	ds_read_b128 v[168:171], v155 offset:1024
	ds_read_b128 v[172:175], v155 offset:2048
	ds_read_b128 v[176:179], v155 offset:3072
	ds_read_b128 v[180:183], v155 offset:16384
	ds_read_b128 v[184:187], v155 offset:17408
	ds_read_b128 v[188:191], v155 offset:18432
	ds_read_b128 v[192:195], v155 offset:19456
	s_add_i32 m0, s48, 0xc000
	ds_read_b128 v[196:199], v157
	ds_read_b128 v[200:203], v157 offset:1024
	ds_read_b128 v[204:207], v157 offset:2048
	ds_read_b128 v[220:223], v157 offset:3072
	ds_read_b128 v[236:239], v157 offset:4096
	ds_read_b128 v[240:243], v157 offset:5120
	ds_read_b128 v[244:247], v157 offset:6144
	ds_read_b128 v[248:251], v157 offset:7168
	global_load_lds_dwordx4 v140, s[30:31]
	s_add_i32 m0, s48, 0xe000
	s_nop 0
	global_load_lds_dwordx4 v138, s[30:31]
	s_branch .Lpadj_12
	s_nop 0
	s_nop 0
	s_nop 0
	s_nop 0
	s_nop 0
	s_nop 0
	s_nop 0
	s_nop 0
	s_nop 0
	s_nop 0
	s_nop 0
	s_nop 0
	s_nop 0
	s_nop 0

.Lpadj_13:
	s_waitcnt vmcnt(8)
	s_waitcnt lgkmcnt(0)
	s_barrier
	v_mfma_f32_16x16x32_bf16 v[62:65], v[142:145], v[196:199], v[62:65]
	v_mfma_f32_16x16x32_bf16 v[54:57], v[172:175], v[196:199], v[54:57]
	v_mfma_f32_16x16x32_bf16 v[46:49], v[142:145], v[204:207], v[46:49]
	v_mfma_f32_16x16x32_bf16 v[38:41], v[172:175], v[204:207], v[38:41]
	v_mfma_f32_16x16x32_bf16 v[30:33], v[142:145], v[236:239], v[30:33]
	v_mfma_f32_16x16x32_bf16 v[22:25], v[172:175], v[236:239], v[22:25]
	v_mfma_f32_16x16x32_bf16 v[14:17], v[142:145], v[244:247], v[14:17]
	v_mfma_f32_16x16x32_bf16 v[6:9], v[172:175], v[244:247], v[6:9]
	v_mfma_f32_16x16x32_bf16 v[62:65], v[168:171], v[200:203], v[62:65]
	v_mfma_f32_16x16x32_bf16 v[54:57], v[176:179], v[200:203], v[54:57]
	v_mfma_f32_16x16x32_bf16 v[46:49], v[168:171], v[220:223], v[46:49]
	v_mfma_f32_16x16x32_bf16 v[38:41], v[176:179], v[220:223], v[38:41]
	v_mfma_f32_16x16x32_bf16 v[30:33], v[168:171], v[240:243], v[30:33]
	v_mfma_f32_16x16x32_bf16 v[22:25], v[176:179], v[240:243], v[22:25]
	v_mfma_f32_16x16x32_bf16 v[14:17], v[168:171], v[248:251], v[14:17]
	v_mfma_f32_16x16x32_bf16 v[6:9], v[176:179], v[248:251], v[6:9]
	v_mfma_f32_16x16x32_bf16 v[58:61], v[180:183], v[196:199], v[58:61]
	v_mfma_f32_16x16x32_bf16 v[50:53], v[188:191], v[196:199], v[50:53]
	v_mfma_f32_16x16x32_bf16 v[42:45], v[180:183], v[204:207], v[42:45]
	v_mfma_f32_16x16x32_bf16 v[34:37], v[188:191], v[204:207], v[34:37]
	v_mfma_f32_16x16x32_bf16 v[26:29], v[180:183], v[236:239], v[26:29]
	v_mfma_f32_16x16x32_bf16 v[18:21], v[188:191], v[236:239], v[18:21]
	v_mfma_f32_16x16x32_bf16 v[10:13], v[180:183], v[244:247], v[10:13]
	v_mfma_f32_16x16x32_bf16 v[2:5], v[188:191], v[244:247], v[2:5]
	v_mfma_f32_16x16x32_bf16 v[58:61], v[184:187], v[200:203], v[58:61]
	v_mfma_f32_16x16x32_bf16 v[50:53], v[192:195], v[200:203], v[50:53]
	v_mfma_f32_16x16x32_bf16 v[42:45], v[184:187], v[220:223], v[42:45]
	v_mfma_f32_16x16x32_bf16 v[34:37], v[192:195], v[220:223], v[34:37]
	v_mfma_f32_16x16x32_bf16 v[26:29], v[184:187], v[240:243], v[26:29]
	v_mfma_f32_16x16x32_bf16 v[18:21], v[192:195], v[240:243], v[18:21]
	v_mfma_f32_16x16x32_bf16 v[10:13], v[184:187], v[248:251], v[10:13]
	v_mfma_f32_16x16x32_bf16 v[2:5], v[192:195], v[248:251], v[2:5]
	s_barrier
	s_add_i32 s57, 0, 0x18000
	s_add_i32 s58, 0, 0x1c000
	ds_read_b128 v[142:145], v155 offset:32768
	ds_read_b128 v[168:171], v155 offset:33792
	ds_read_b128 v[172:175], v155 offset:34816
	ds_read_b128 v[176:179], v155 offset:35840
	ds_read_b128 v[180:183], v155 offset:49152
	ds_read_b128 v[184:187], v155 offset:50176
	ds_read_b128 v[188:191], v155 offset:51200
	ds_read_b128 v[192:195], v155 offset:52224
	s_add_u32 s36, s36, 0x40000
	s_addc_u32 s37, s37, 0
	s_mov_b32 m0, s50
	ds_read_b128 v[196:199], v157 offset:32768
	ds_read_b128 v[200:203], v157 offset:33792
	ds_read_b128 v[204:207], v157 offset:34816
	ds_read_b128 v[220:223], v157 offset:35840
	ds_read_b128 v[236:239], v157 offset:36864
	ds_read_b128 v[240:243], v157 offset:37888
	ds_read_b128 v[244:247], v157 offset:38912
	ds_read_b128 v[248:251], v157 offset:39936
	global_load_lds_dwordx4 v136, s[36:37]
	s_mov_b32 m0, s51
	s_nop 0
	global_load_lds_dwordx4 v132, s[36:37]
	s_branch .Lpadj_14
	s_nop 0
	s_nop 0
	s_nop 0
	s_nop 0
	s_nop 0
	s_nop 0
	s_nop 0
	s_nop 0
	s_nop 0
	s_nop 0
	s_nop 0
	s_nop 0
	s_nop 0

.LBB0_463:
	v_mov_b32_e32 v133, v0
	v_lshl_add_u64 v[8:9], s[26:27], 0, v[132:133]
	v_mov_b32_e32 v137, v0
	v_lshl_add_u64 v[10:11], s[26:27], 0, v[136:137]
	v_mov_b32_e32 v131, v0
	s_add_i32 m0, s51, 0x18000
	v_lshl_add_u64 v[8:9], v[8:9], 0, s[96:97]
	v_lshl_add_u64 v[16:17], s[28:29], 0, v[130:131]
	v_mov_b32_e32 v135, v0
	s_waitcnt vmcnt(2)
	s_barrier
	global_load_lds_dwordx4 v[8:9], off
	v_lshl_add_u64 v[8:9], v[10:11], 0, s[96:97]
	s_add_i32 m0, s51, 0x1a000
	s_add_i32 s57, s51, 0x8000
	v_lshl_add_u64 v[18:19], s[28:29], 0, v[134:135]
	global_load_lds_dwordx4 v[8:9], off
	v_lshl_add_u64 v[8:9], v[16:17], 0, s[96:97]
	s_mov_b32 m0, s57
	s_add_i32 s58, s51, 0xa000
	v_lshl_add_u64 v[12:13], s[4:5], 0, v[132:133]
	global_load_lds_dwordx4 v[8:9], off
	v_lshl_add_u64 v[8:9], v[18:19], 0, s[96:97]
	s_mov_b32 m0, s58
	v_lshl_add_u64 v[14:15], s[4:5], 0, v[136:137]
	global_load_lds_dwordx4 v[8:9], off
	s_add_i32 m0, s51, 0x1c000
	v_lshl_add_u64 v[8:9], v[12:13], 0, s[96:97]
	global_load_lds_dwordx4 v[8:9], off
	v_lshl_add_u64 v[8:9], v[14:15], 0, s[96:97]
	s_add_i32 m0, s51, 0x1e000
	v_and_b32_e32 v1, 15, v233
	global_load_lds_dwordx4 v[8:9], off
	v_and_b32_e32 v20, 48, v233
	v_lshlrev_b32_e32 v21, 2, v233
	s_and_b32 s41, s13, 3
	s_lshr_b32 s56, s6, 6
	s_lshl_b32 s4, s40, 13
	v_lshl_or_b32 v20, v1, 6, v20
	v_and_b32_e32 v21, 32, v21
	s_lshr_b32 s7, s7, 3
	s_lshl_b32 s12, s40, 6
	v_bitop3_b32 v22, v20, s4, v21 bitop3:0xde
	s_lshl_b32 s4, s41, 12
	s_add_i32 s59, s56, -2
	v_bitop3_b32 v146, s4, v20, v21 bitop3:0xf6
	v_add_u32_e32 v146, 0x10000, v146
	s_add_u32 s4, s45, 0x80
	v_add_u32_e32 v2, v4, v2
	s_waitcnt vmcnt(6)
	s_addc_u32 s5, 0, 0
	v_add_u32_e32 v5, v7, v5
	v_add_lshl_u32 v2, v2, v3, 1
	v_mov_b32_e32 v3, v0
	v_add_lshl_u32 v6, v5, v6, 1
	v_mov_b32_e32 v7, v0
	v_lshl_add_u64 v[140:141], s[4:5], 0, v[2:3]
	v_mov_b32_e32 v2, 0
	s_sext_i32_i8 s55, s7
	v_or_b32_e32 v235, s12, v1
	v_lshl_add_u64 v[138:139], s[4:5], 0, v[6:7]
	s_mov_b32 s60, 0
	v_add_u32_e32 v147, 0, v22
	v_mov_b32_e32 v3, v2
	v_mov_b32_e32 v4, v2
	v_mov_b32_e32 v5, v2
	v_mov_b32_e32 v6, v2
	v_mov_b32_e32 v7, v2
	v_mov_b32_e32 v8, v2
	v_mov_b32_e32 v9, v2
	v_mov_b32_e32 v18, v2
	v_mov_b32_e32 v19, v2
	v_mov_b32_e32 v20, v2
	v_mov_b32_e32 v21, v2
	v_mov_b32_e32 v22, v2
	v_mov_b32_e32 v23, v2
	v_mov_b32_e32 v24, v2
	v_mov_b32_e32 v25, v2
	v_mov_b32_e32 v34, v2
	v_mov_b32_e32 v35, v2
	v_mov_b32_e32 v36, v2
	v_mov_b32_e32 v37, v2
	v_mov_b32_e32 v38, v2
	v_mov_b32_e32 v39, v2
	v_mov_b32_e32 v40, v2
	v_mov_b32_e32 v41, v2
	v_mov_b32_e32 v50, v2
	v_mov_b32_e32 v51, v2
	v_mov_b32_e32 v52, v2
	v_mov_b32_e32 v53, v2
	v_mov_b32_e32 v54, v2
	v_mov_b32_e32 v55, v2
	v_mov_b32_e32 v56, v2
	v_mov_b32_e32 v57, v2
	v_mov_b32_e32 v10, v2
	v_mov_b32_e32 v11, v2
	v_mov_b32_e32 v12, v2
	v_mov_b32_e32 v13, v2
	v_mov_b32_e32 v14, v2
	v_mov_b32_e32 v15, v2
	v_mov_b32_e32 v16, v2
	v_mov_b32_e32 v17, v2
	v_mov_b32_e32 v26, v2
	v_mov_b32_e32 v27, v2
	v_mov_b32_e32 v28, v2
	v_mov_b32_e32 v29, v2
	v_mov_b32_e32 v30, v2
	v_mov_b32_e32 v31, v2
	v_mov_b32_e32 v32, v2
	v_mov_b32_e32 v33, v2
	v_mov_b32_e32 v42, v2
	v_mov_b32_e32 v43, v2
	v_mov_b32_e32 v44, v2
	v_mov_b32_e32 v45, v2
	v_mov_b32_e32 v46, v2
	v_mov_b32_e32 v47, v2
	v_mov_b32_e32 v48, v2
	v_mov_b32_e32 v49, v2
	v_mov_b32_e32 v58, v2
	v_mov_b32_e32 v59, v2
	v_mov_b32_e32 v60, v2
	v_mov_b32_e32 v61, v2
	v_mov_b32_e32 v62, v2
	v_mov_b32_e32 v63, v2
	v_mov_b32_e32 v64, v2
	v_mov_b32_e32 v65, v2
	v_mov_b32_e32 v66, v2
	v_mov_b32_e32 v67, v2
	v_mov_b32_e32 v68, v2
	v_mov_b32_e32 v69, v2
	v_mov_b32_e32 v70, v2
	v_mov_b32_e32 v71, v2
	v_mov_b32_e32 v72, v2
	v_mov_b32_e32 v73, v2
	v_mov_b32_e32 v82, v2
	v_mov_b32_e32 v83, v2
	v_mov_b32_e32 v84, v2
	v_mov_b32_e32 v85, v2
	v_mov_b32_e32 v86, v2
	v_mov_b32_e32 v87, v2
	v_mov_b32_e32 v88, v2
	v_mov_b32_e32 v89, v2
	v_mov_b32_e32 v98, v2
	v_mov_b32_e32 v99, v2
	v_mov_b32_e32 v100, v2
	v_mov_b32_e32 v101, v2
	v_mov_b32_e32 v102, v2
	v_mov_b32_e32 v103, v2
	v_mov_b32_e32 v104, v2
	v_mov_b32_e32 v105, v2
	v_mov_b32_e32 v114, v2
	v_mov_b32_e32 v115, v2
	v_mov_b32_e32 v116, v2
	v_mov_b32_e32 v117, v2
	v_mov_b32_e32 v118, v2
	v_mov_b32_e32 v119, v2
	v_mov_b32_e32 v120, v2
	v_mov_b32_e32 v121, v2
	v_mov_b32_e32 v74, v2
	v_mov_b32_e32 v75, v2
	v_mov_b32_e32 v76, v2
	v_mov_b32_e32 v77, v2
	v_mov_b32_e32 v78, v2
	v_mov_b32_e32 v79, v2
	v_mov_b32_e32 v80, v2
	v_mov_b32_e32 v81, v2
	v_mov_b32_e32 v90, v2
	v_mov_b32_e32 v91, v2
	v_mov_b32_e32 v92, v2
	v_mov_b32_e32 v93, v2
	v_mov_b32_e32 v94, v2
	v_mov_b32_e32 v95, v2
	v_mov_b32_e32 v96, v2
	v_mov_b32_e32 v97, v2
	v_mov_b32_e32 v106, v2
	v_mov_b32_e32 v107, v2
	v_mov_b32_e32 v108, v2
	v_mov_b32_e32 v109, v2
	v_mov_b32_e32 v110, v2
	v_mov_b32_e32 v111, v2
	v_mov_b32_e32 v112, v2
	v_mov_b32_e32 v113, v2
	v_mov_b32_e32 v122, v2
	v_mov_b32_e32 v123, v2
	v_mov_b32_e32 v124, v2
	v_mov_b32_e32 v125, v2
	v_mov_b32_e32 v126, v2
	v_mov_b32_e32 v127, v2
	v_mov_b32_e32 v128, v2
	v_mov_b32_e32 v129, v2
	s_barrier
	s_branch .LBB0_465

.LBB0_476:
	s_add_i32 s63, s31, 2
	s_add_u32 s38, s28, s36
	s_addc_u32 s39, s29, s37
	s_add_u32 s64, s26, s36
	s_addc_u32 s65, s27, s37
	s_add_i32 s66, 0, 0x10000
	s_cmp_eq_u32 s59, s31
	s_cselect_b32 s39, s9, s39
	s_cselect_b32 s38, s8, s38
	s_cselect_b32 s65, s35, s65
	s_cselect_b32 s64, s34, s64
	s_add_i32 s31, 0, 0x14000
	ds_read_b128 v[148:151], v146
	ds_read_b128 v[152:155], v146 offset:1024
	ds_read_b128 v[156:159], v146 offset:2048
	ds_read_b128 v[160:163], v146 offset:3072
	ds_read_b128 v[164:167], v146 offset:16384
	ds_read_b128 v[168:171], v146 offset:17408
	ds_read_b128 v[172:175], v146 offset:18432
	ds_read_b128 v[176:179], v146 offset:19456
	v_lshl_add_u64 v[208:209], s[28:29], 0, v[142:143]
	s_add_i32 m0, s51, 0xc000
	ds_read_b128 v[180:183], v147
	ds_read_b128 v[184:187], v147 offset:1024
	ds_read_b128 v[188:191], v147 offset:2048
	ds_read_b128 v[192:195], v147 offset:3072
	ds_read_b128 v[196:199], v147 offset:4096
	ds_read_b128 v[200:203], v147 offset:5120
	ds_read_b128 v[204:207], v147 offset:6144
	ds_read_b128 v[220:223], v147 offset:7168
	global_load_lds_dwordx4 v[208:209], off
	s_add_i32 m0, s51, 0xe000
	v_lshl_add_u64 v[208:209], s[28:29], 0, v[144:145]
	global_load_lds_dwordx4 v[208:209], off
	s_branch .Lpadj_16
	s_nop 0
	s_nop 0
	s_nop 0
	s_nop 0
	s_nop 0
	s_nop 0
	s_nop 0
	s_nop 0
	s_nop 0
	s_nop 0
	s_nop 0

.Lpadj_17:
	s_waitcnt vmcnt(8)
	s_waitcnt lgkmcnt(0)
	s_barrier
	v_mfma_f32_16x16x32_bf16 v[62:65], v[148:151], v[180:183], v[62:65]
	v_mfma_f32_16x16x32_bf16 v[58:61], v[156:159], v[180:183], v[58:61]
	v_mfma_f32_16x16x32_bf16 v[46:49], v[148:151], v[188:191], v[46:49]
	v_mfma_f32_16x16x32_bf16 v[42:45], v[156:159], v[188:191], v[42:45]
	v_mfma_f32_16x16x32_bf16 v[30:33], v[148:151], v[196:199], v[30:33]
	v_mfma_f32_16x16x32_bf16 v[26:29], v[156:159], v[196:199], v[26:29]
	v_mfma_f32_16x16x32_bf16 v[14:17], v[148:151], v[204:207], v[14:17]
	v_mfma_f32_16x16x32_bf16 v[10:13], v[156:159], v[204:207], v[10:13]
	v_mfma_f32_16x16x32_bf16 v[62:65], v[152:155], v[184:187], v[62:65]
	v_mfma_f32_16x16x32_bf16 v[58:61], v[160:163], v[184:187], v[58:61]
	v_mfma_f32_16x16x32_bf16 v[46:49], v[152:155], v[192:195], v[46:49]
	v_mfma_f32_16x16x32_bf16 v[42:45], v[160:163], v[192:195], v[42:45]
	v_mfma_f32_16x16x32_bf16 v[30:33], v[152:155], v[200:203], v[30:33]
	v_mfma_f32_16x16x32_bf16 v[26:29], v[160:163], v[200:203], v[26:29]
	v_mfma_f32_16x16x32_bf16 v[14:17], v[152:155], v[220:223], v[14:17]
	v_mfma_f32_16x16x32_bf16 v[10:13], v[160:163], v[220:223], v[10:13]
	v_mfma_f32_16x16x32_bf16 v[54:57], v[164:167], v[180:183], v[54:57]
	v_mfma_f32_16x16x32_bf16 v[50:53], v[172:175], v[180:183], v[50:53]
	v_mfma_f32_16x16x32_bf16 v[38:41], v[164:167], v[188:191], v[38:41]
	v_mfma_f32_16x16x32_bf16 v[34:37], v[172:175], v[188:191], v[34:37]
	v_mfma_f32_16x16x32_bf16 v[22:25], v[164:167], v[196:199], v[22:25]
	v_mfma_f32_16x16x32_bf16 v[18:21], v[172:175], v[196:199], v[18:21]
	v_mfma_f32_16x16x32_bf16 v[6:9], v[164:167], v[204:207], v[6:9]
	v_mfma_f32_16x16x32_bf16 v[2:5], v[172:175], v[204:207], v[2:5]
	v_mfma_f32_16x16x32_bf16 v[54:57], v[168:171], v[184:187], v[54:57]
	v_mfma_f32_16x16x32_bf16 v[50:53], v[176:179], v[184:187], v[50:53]
	v_mfma_f32_16x16x32_bf16 v[38:41], v[168:171], v[192:195], v[38:41]
	v_mfma_f32_16x16x32_bf16 v[34:37], v[176:179], v[192:195], v[34:37]
	v_mfma_f32_16x16x32_bf16 v[22:25], v[168:171], v[200:203], v[22:25]
	v_mfma_f32_16x16x32_bf16 v[18:21], v[176:179], v[200:203], v[18:21]
	v_mfma_f32_16x16x32_bf16 v[6:9], v[168:171], v[220:223], v[6:9]
	v_mfma_f32_16x16x32_bf16 v[2:5], v[176:179], v[220:223], v[2:5]
	s_barrier
	s_add_i32 s31, 0, 0x18000
	s_add_i32 s64, 0, 0x1c000
	ds_read_b128 v[148:151], v146 offset:32768
	ds_read_b128 v[152:155], v146 offset:33792
	ds_read_b128 v[156:159], v146 offset:34816
	ds_read_b128 v[160:163], v146 offset:35840
	ds_read_b128 v[164:167], v146 offset:49152
	ds_read_b128 v[168:171], v146 offset:50176
	ds_read_b128 v[172:175], v146 offset:51200
	ds_read_b128 v[176:179], v146 offset:52224
	s_add_u32 s38, s38, s45
	s_addc_u32 s39, s39, 0
	s_mov_b32 m0, s53
	ds_read_b128 v[180:183], v147 offset:32768
	ds_read_b128 v[184:187], v147 offset:33792
	ds_read_b128 v[188:191], v147 offset:34816
	ds_read_b128 v[192:195], v147 offset:35840
	ds_read_b128 v[196:199], v147 offset:36864
	ds_read_b128 v[200:203], v147 offset:37888
	ds_read_b128 v[204:207], v147 offset:38912
	ds_read_b128 v[220:223], v147 offset:39936
	global_load_lds_dwordx4 v130, s[38:39]
	s_mov_b32 m0, s54
	s_nop 0
	global_load_lds_dwordx4 v134, s[38:39]
	s_branch .Lpadj_18
	s_nop 0
	s_nop 0
	s_nop 0
	s_nop 0
	s_nop 0
	s_nop 0
	s_nop 0
	s_nop 0
	s_nop 0
	s_nop 0
	s_nop 0
	s_nop 0
	s_nop 0
	s_nop 0

.LBB0_634:
	s_lshl_b32 s8, s8, 5
	s_and_b32 s11, s8, 0x60
	s_add_i32 m0, s30, 0x18000
	v_lshl_add_u64 v[8:9], v[8:9], 0, s[96:97]
	s_lshl_b32 s10, s9, 13
	s_lshl_b32 s12, s11, 7
	s_waitcnt vmcnt(2)
	s_barrier
	global_load_lds_dwordx4 v[8:9], off
	v_lshl_add_u64 v[6:7], v[6:7], 0, s[96:97]
	s_add_i32 m0, s30, 0x1a000
	s_add_i32 s36, s30, 0x8000
	s_add_i32 s37, s30, 0xa000
	global_load_lds_dwordx4 v[6:7], off
	v_lshl_add_u64 v[2:3], v[2:3], 0, s[96:97]
	s_mov_b32 m0, s36
	s_add_u32 s8, s20, 0x40080
	global_load_lds_dwordx4 v[2:3], off
	v_lshl_add_u64 v[2:3], v[4:5], 0, s[96:97]
	s_mov_b32 m0, s37
	s_addc_u32 s9, s21, 0
	global_load_lds_dwordx4 v[2:3], off
	s_add_i32 m0, s30, 0x1c000
	v_lshl_add_u64 v[2:3], s[8:9], 0, v[134:135]
	global_load_lds_dwordx4 v[2:3], off
	v_lshl_add_u64 v[2:3], s[8:9], 0, v[130:131]
	s_add_i32 m0, s30, 0x1e000
	s_sext_i32_i8 s40, s4
	global_load_lds_dwordx4 v[2:3], off
	v_lshrrev_b32_e32 v2, 1, v233
	v_and_b32_e32 v2, 24, v2
	v_lshlrev_b32_e32 v3, 6, v1
	v_lshlrev_b32_e32 v4, 1, v2
	s_movk_i32 s4, 0x3c0
	v_lshlrev_b32_e32 v5, 2, v1
	v_and_or_b32 v3, v3, s4, v4
	v_and_b32_e32 v5, 32, v5
	v_bitop3_b32 v3, v3, s10, v5 bitop3:0xde
	v_lshlrev_b32_e32 v5, 2, v11
	v_or_b32_e32 v160, s11, v2
	v_lshlrev_b32_e32 v2, 14, v10
	v_lshl_or_b32 v4, v11, 6, v4
	v_and_b32_e32 v5, 32, v5
	v_and_b32_e32 v2, 0xffff8000, v2
	v_bitop3_b32 v159, s12, v4, v5 bitop3:0xf6
	v_add_u32_e32 v159, 0x10000, v159
	v_lshl_add_u32 v2, v12, 11, v2
	v_and_b32_e32 v4, 1, v10
	v_lshl_or_b32 v2, v4, 6, v2
	v_lshl_add_u32 v138, v13, 1, v2
	v_lshlrev_b32_e32 v2, 14, v15
	v_and_b32_e32 v2, 0xffff8000, v2
	s_waitcnt vmcnt(6)
	v_lshl_add_u32 v2, v14, 11, v2
	v_and_b32_e32 v4, 1, v15
	s_cmpk_lt_u32 s5, 0x100
	v_lshl_or_b32 v2, v4, 6, v2
	v_or_b32_e32 v161, 0xfffffe00, v160
	s_cselect_b64 s[8:9], -1, 0
	s_ashr_i32 s38, s98, 31
	v_mov_b32_e32 v139, v0
	v_lshl_add_u32 v140, v16, 1, v2
	v_mov_b32_e32 v141, v0
	s_mov_b32 s39, 0
	v_add_u32_e32 v162, 0, v3
	s_barrier
	s_branch .LBB0_637

.LBB0_639:
	s_ashr_i32 s13, s12, 31
	s_lshl_b64 s[14:15], s[12:13], 19
	s_add_u32 s14, s80, s14
	s_addc_u32 s15, s81, s15
	s_and_b64 s[16:17], s[4:5], exec
	s_cselect_b32 s13, s15, s23
	s_cselect_b32 s19, s14, s22
	s_ashr_i32 s11, s10, 31
	s_lshl_b64 s[16:17], s[10:11], 19
	s_add_u32 s16, s26, s16
	s_addc_u32 s17, s27, s17
	s_and_b64 s[24:25], s[4:5], exec
	s_cselect_b32 s11, s17, s21
	s_cselect_b32 s41, s16, s20
	s_add_u32 s43, s20, 0x100
	s_addc_u32 s44, s21, 0
	s_add_u32 s20, s22, 0x40080
	s_addc_u32 s21, s23, 0
	s_mov_b32 s45, -2
	s_add_u32 s22, s20, 0xfffc0080
	s_addc_u32 s23, s21, -1
	s_add_i32 s46, 0, 0x10000
	s_cmp_eq_u32 s45, 12
	s_cselect_b32 s25, s13, s23
	s_cselect_b32 s24, s19, s22
	s_cselect_b32 s23, s11, s44
	s_cselect_b32 s22, s41, s43
	s_add_i32 s48, 0, 0x14000
	ds_read_b128 v[164:167], v159
	ds_read_b128 v[168:171], v159 offset:1024
	ds_read_b128 v[172:175], v159 offset:2048
	ds_read_b128 v[176:179], v159 offset:3072
	ds_read_b128 v[180:183], v159 offset:16384
	ds_read_b128 v[184:187], v159 offset:17408
	ds_read_b128 v[188:191], v159 offset:18432
	ds_read_b128 v[192:195], v159 offset:19456
	v_lshl_add_u64 v[150:151], s[20:21], 0, v[140:141]
	s_add_i32 m0, s30, 0xc000
	ds_read_b128 v[196:199], v162
	ds_read_b128 v[200:203], v162 offset:1024
	ds_read_b128 v[204:207], v162 offset:2048
	ds_read_b128 v[220:223], v162 offset:3072
	ds_read_b128 v[236:239], v162 offset:4096
	ds_read_b128 v[240:243], v162 offset:5120
	ds_read_b128 v[244:247], v162 offset:6144
	ds_read_b128 v[248:251], v162 offset:7168
	global_load_lds_dwordx4 v[150:151], off
	s_add_i32 m0, s30, 0xe000
	v_lshl_add_u64 v[150:151], s[20:21], 0, v[138:139]
	global_load_lds_dwordx4 v[150:151], off
	s_branch .Lpadj_20
	s_nop 0
	s_nop 0
	s_nop 0
	s_nop 0
	s_nop 0
	s_nop 0
	s_nop 0
	s_nop 0
	s_nop 0

.Lpadj_21:
	s_waitcnt vmcnt(8)
	s_waitcnt lgkmcnt(0)
	s_barrier
	v_mfma_f32_16x16x32_bf16 v[62:65], v[164:167], v[196:199], 0
	v_mfma_f32_16x16x32_bf16 v[58:61], v[172:175], v[196:199], 0
	v_mfma_f32_16x16x32_bf16 v[54:57], v[164:167], v[204:207], 0
	v_mfma_f32_16x16x32_bf16 v[50:53], v[172:175], v[204:207], 0
	v_mfma_f32_16x16x32_bf16 v[46:49], v[164:167], v[236:239], 0
	v_mfma_f32_16x16x32_bf16 v[42:45], v[172:175], v[236:239], 0
	v_mfma_f32_16x16x32_bf16 v[38:41], v[164:167], v[244:247], 0
	v_mfma_f32_16x16x32_bf16 v[34:37], v[172:175], v[244:247], 0
	v_mfma_f32_16x16x32_bf16 v[62:65], v[168:171], v[200:203], v[62:65]
	v_mfma_f32_16x16x32_bf16 v[58:61], v[176:179], v[200:203], v[58:61]
	v_mfma_f32_16x16x32_bf16 v[54:57], v[168:171], v[220:223], v[54:57]
	v_mfma_f32_16x16x32_bf16 v[50:53], v[176:179], v[220:223], v[50:53]
	v_mfma_f32_16x16x32_bf16 v[46:49], v[168:171], v[240:243], v[46:49]
	v_mfma_f32_16x16x32_bf16 v[42:45], v[176:179], v[240:243], v[42:45]
	v_mfma_f32_16x16x32_bf16 v[38:41], v[168:171], v[248:251], v[38:41]
	v_mfma_f32_16x16x32_bf16 v[34:37], v[176:179], v[248:251], v[34:37]
	v_mfma_f32_16x16x32_bf16 v[30:33], v[180:183], v[196:199], 0
	v_mfma_f32_16x16x32_bf16 v[26:29], v[188:191], v[196:199], 0
	v_mfma_f32_16x16x32_bf16 v[22:25], v[180:183], v[204:207], 0
	v_mfma_f32_16x16x32_bf16 v[18:21], v[188:191], v[204:207], 0
	v_mfma_f32_16x16x32_bf16 v[14:17], v[180:183], v[236:239], 0
	v_mfma_f32_16x16x32_bf16 v[10:13], v[188:191], v[236:239], 0
	v_mfma_f32_16x16x32_bf16 v[6:9], v[180:183], v[244:247], 0
	v_mfma_f32_16x16x32_bf16 v[2:5], v[188:191], v[244:247], 0
	v_mfma_f32_16x16x32_bf16 v[30:33], v[184:187], v[200:203], v[30:33]
	v_mfma_f32_16x16x32_bf16 v[26:29], v[192:195], v[200:203], v[26:29]
	v_mfma_f32_16x16x32_bf16 v[22:25], v[184:187], v[220:223], v[22:25]
	v_mfma_f32_16x16x32_bf16 v[18:21], v[192:195], v[220:223], v[18:21]
	v_mfma_f32_16x16x32_bf16 v[14:17], v[184:187], v[240:243], v[14:17]
	v_mfma_f32_16x16x32_bf16 v[10:13], v[192:195], v[240:243], v[10:13]
	v_mfma_f32_16x16x32_bf16 v[6:9], v[184:187], v[248:251], v[6:9]
	v_mfma_f32_16x16x32_bf16 v[2:5], v[192:195], v[248:251], v[2:5]
	s_barrier
	s_add_i32 s46, 0, 0x18000
	s_add_i32 s47, 0, 0x1c000
	ds_read_b128 v[164:167], v159 offset:32768
	ds_read_b128 v[168:171], v159 offset:33792
	ds_read_b128 v[172:175], v159 offset:34816
	ds_read_b128 v[176:179], v159 offset:35840
	ds_read_b128 v[180:183], v159 offset:49152
	ds_read_b128 v[184:187], v159 offset:50176
	ds_read_b128 v[188:191], v159 offset:51200
	ds_read_b128 v[192:195], v159 offset:52224
	s_add_u32 s24, s24, 0x40000
	s_addc_u32 s25, s25, 0
	s_mov_b32 m0, s34
	v_lshl_add_u64 v[230:231], s[24:25], 0, v[136:137]
	ds_read_b128 v[196:199], v162 offset:32768
	ds_read_b128 v[200:203], v162 offset:33792
	ds_read_b128 v[204:207], v162 offset:34816
	ds_read_b128 v[220:223], v162 offset:35840
	ds_read_b128 v[236:239], v162 offset:36864
	ds_read_b128 v[240:243], v162 offset:37888
	ds_read_b128 v[244:247], v162 offset:38912
	ds_read_b128 v[248:251], v162 offset:39936
	global_load_lds_dwordx4 v[230:231], off
	s_mov_b32 m0, s35
	v_lshl_add_u64 v[230:231], s[24:25], 0, v[132:133]
	global_load_lds_dwordx4 v[230:231], off
	s_branch .Lpadj_22
	s_nop 0
	s_nop 0
	s_nop 0
	s_nop 0
	s_nop 0
	s_nop 0
	s_nop 0
	s_nop 0
	s_nop 0
	s_nop 0

.LBB0_640:
	s_add_u32 s22, s20, 0xfffc0080
	s_addc_u32 s23, s21, -1
	s_add_i32 s46, 0, 0x10000
	s_cmp_eq_u32 s45, 12
	s_cselect_b32 s25, s13, s23
	s_cselect_b32 s24, s19, s22
	s_cselect_b32 s23, s11, s44
	s_cselect_b32 s22, s41, s43
	s_add_i32 s48, 0, 0x14000
	ds_read_b128 v[164:167], v159
	ds_read_b128 v[168:171], v159 offset:1024
	ds_read_b128 v[172:175], v159 offset:2048
	ds_read_b128 v[176:179], v159 offset:3072
	ds_read_b128 v[180:183], v159 offset:16384
	ds_read_b128 v[184:187], v159 offset:17408
	ds_read_b128 v[188:191], v159 offset:18432
	ds_read_b128 v[192:195], v159 offset:19456
	s_add_i32 m0, s30, 0xc000
	ds_read_b128 v[196:199], v162
	ds_read_b128 v[200:203], v162 offset:1024
	ds_read_b128 v[204:207], v162 offset:2048
	ds_read_b128 v[220:223], v162 offset:3072
	ds_read_b128 v[236:239], v162 offset:4096
	ds_read_b128 v[240:243], v162 offset:5120
	ds_read_b128 v[244:247], v162 offset:6144
	ds_read_b128 v[248:251], v162 offset:7168
	global_load_lds_dwordx4 v140, s[20:21]
	s_add_i32 m0, s30, 0xe000
	s_nop 0
	global_load_lds_dwordx4 v138, s[20:21]
	s_branch .Lpadj_24
	s_nop 0
	s_nop 0
	s_nop 0
	s_nop 0
	s_nop 0
	s_nop 0
	s_nop 0
	s_nop 0
	s_nop 0
	s_nop 0
	s_nop 0
	s_nop 0
	s_nop 0
	s_nop 0

.Lpadj_25:
	s_waitcnt vmcnt(8)
	s_waitcnt lgkmcnt(0)
	s_barrier
	v_mfma_f32_16x16x32_bf16 v[62:65], v[164:167], v[196:199], v[62:65]
	v_mfma_f32_16x16x32_bf16 v[58:61], v[172:175], v[196:199], v[58:61]
	v_mfma_f32_16x16x32_bf16 v[54:57], v[164:167], v[204:207], v[54:57]
	v_mfma_f32_16x16x32_bf16 v[50:53], v[172:175], v[204:207], v[50:53]
	v_mfma_f32_16x16x32_bf16 v[46:49], v[164:167], v[236:239], v[46:49]
	v_mfma_f32_16x16x32_bf16 v[42:45], v[172:175], v[236:239], v[42:45]
	v_mfma_f32_16x16x32_bf16 v[38:41], v[164:167], v[244:247], v[38:41]
	v_mfma_f32_16x16x32_bf16 v[34:37], v[172:175], v[244:247], v[34:37]
	v_mfma_f32_16x16x32_bf16 v[62:65], v[168:171], v[200:203], v[62:65]
	v_mfma_f32_16x16x32_bf16 v[58:61], v[176:179], v[200:203], v[58:61]
	v_mfma_f32_16x16x32_bf16 v[54:57], v[168:171], v[220:223], v[54:57]
	v_mfma_f32_16x16x32_bf16 v[50:53], v[176:179], v[220:223], v[50:53]
	v_mfma_f32_16x16x32_bf16 v[46:49], v[168:171], v[240:243], v[46:49]
	v_mfma_f32_16x16x32_bf16 v[42:45], v[176:179], v[240:243], v[42:45]
	v_mfma_f32_16x16x32_bf16 v[38:41], v[168:171], v[248:251], v[38:41]
	v_mfma_f32_16x16x32_bf16 v[34:37], v[176:179], v[248:251], v[34:37]
	v_mfma_f32_16x16x32_bf16 v[30:33], v[180:183], v[196:199], v[30:33]
	v_mfma_f32_16x16x32_bf16 v[26:29], v[188:191], v[196:199], v[26:29]
	v_mfma_f32_16x16x32_bf16 v[22:25], v[180:183], v[204:207], v[22:25]
	v_mfma_f32_16x16x32_bf16 v[18:21], v[188:191], v[204:207], v[18:21]
	v_mfma_f32_16x16x32_bf16 v[14:17], v[180:183], v[236:239], v[14:17]
	v_mfma_f32_16x16x32_bf16 v[10:13], v[188:191], v[236:239], v[10:13]
	v_mfma_f32_16x16x32_bf16 v[6:9], v[180:183], v[244:247], v[6:9]
	v_mfma_f32_16x16x32_bf16 v[2:5], v[188:191], v[244:247], v[2:5]
	v_mfma_f32_16x16x32_bf16 v[30:33], v[184:187], v[200:203], v[30:33]
	v_mfma_f32_16x16x32_bf16 v[26:29], v[192:195], v[200:203], v[26:29]
	v_mfma_f32_16x16x32_bf16 v[22:25], v[184:187], v[220:223], v[22:25]
	v_mfma_f32_16x16x32_bf16 v[18:21], v[192:195], v[220:223], v[18:21]
	v_mfma_f32_16x16x32_bf16 v[14:17], v[184:187], v[240:243], v[14:17]
	v_mfma_f32_16x16x32_bf16 v[10:13], v[192:195], v[240:243], v[10:13]
	v_mfma_f32_16x16x32_bf16 v[6:9], v[184:187], v[248:251], v[6:9]
	v_mfma_f32_16x16x32_bf16 v[2:5], v[192:195], v[248:251], v[2:5]
	s_barrier
	s_add_i32 s46, 0, 0x18000
	s_add_i32 s47, 0, 0x1c000
	ds_read_b128 v[164:167], v159 offset:32768
	ds_read_b128 v[168:171], v159 offset:33792
	ds_read_b128 v[172:175], v159 offset:34816
	ds_read_b128 v[176:179], v159 offset:35840
	ds_read_b128 v[180:183], v159 offset:49152
	ds_read_b128 v[184:187], v159 offset:50176
	ds_read_b128 v[188:191], v159 offset:51200
	ds_read_b128 v[192:195], v159 offset:52224
	s_add_u32 s24, s24, 0x40000
	s_addc_u32 s25, s25, 0
	s_mov_b32 m0, s34
	ds_read_b128 v[196:199], v162 offset:32768
	ds_read_b128 v[200:203], v162 offset:33792
	ds_read_b128 v[204:207], v162 offset:34816
	ds_read_b128 v[220:223], v162 offset:35840
	ds_read_b128 v[236:239], v162 offset:36864
	ds_read_b128 v[240:243], v162 offset:37888
	ds_read_b128 v[244:247], v162 offset:38912
	ds_read_b128 v[248:251], v162 offset:39936
	global_load_lds_dwordx4 v136, s[24:25]
	s_mov_b32 m0, s35
	s_nop 0
	global_load_lds_dwordx4 v132, s[24:25]
	s_branch .Lpadj_26
	s_nop 0
	s_nop 0
	s_nop 0
	s_nop 0
	s_nop 0
	s_nop 0
	s_nop 0
	s_nop 0
	s_nop 0
	s_nop 0
	s_nop 0
	s_nop 0
	s_nop 0
